# final f32 output stores (P17) marked nt
# speedup vs baseline: 1.0368x; 1.0066x over previous
.LBB0_2061:
	s_ashr_i32 s17, s16, 31
	s_lshl_b64 s[16:17], s[16:17], 8
	v_lshl_add_u32 v150, s41, 8, v137
	v_mov_b32_e32 v147, s17
	v_or_b32_e32 v146, s16, v136
	v_ashrrev_i32_e32 v151, 31, v150
	v_lshl_add_u64 v[148:149], v[146:147], 1, s[82:83]
	v_lshlrev_b64 v[152:153], 11, v[150:151]
	v_or_b32_e32 v178, 16, v150
	v_lshl_add_u64 v[152:153], v[148:149], 0, v[152:153]
	v_ashrrev_i32_e32 v179, 31, v178
	global_load_dwordx4 v[158:161], v[152:153], off
	global_load_dwordx4 v[162:165], v[152:153], off offset:256
	v_lshlrev_b64 v[152:153], 11, v[178:179]
	v_or_b32_e32 v190, 32, v150
	v_lshl_add_u64 v[152:153], v[148:149], 0, v[152:153]
	v_ashrrev_i32_e32 v191, 31, v190
	global_load_dwordx4 v[166:169], v[152:153], off
	global_load_dwordx4 v[170:173], v[152:153], off offset:256
	v_lshlrev_b64 v[152:153], 11, v[190:191]
	v_lshl_add_u64 v[180:181], v[148:149], 0, v[152:153]
	global_load_dwordx4 v[174:177], v[180:181], off
	v_or_b32_e32 v152, 48, v150
	v_readlane_b32 s44, v242, 40
	v_ashrrev_i32_e32 v153, 31, v152
	v_readlane_b32 s58, v242, 54
	v_readlane_b32 s59, v242, 55
	v_lshlrev_b64 v[186:187], 12, v[178:179]
	global_load_dwordx4 v[178:181], v[180:181], off offset:256
	v_lshlrev_b64 v[182:183], 12, v[150:151]
	v_lshlrev_b64 v[184:185], 11, v[152:153]
	s_mov_b64 s[18:19], s[58:59]
	v_lshl_add_u64 v[182:183], s[18:19], 0, v[182:183]
	v_lshlrev_b64 v[146:147], 2, v[146:147]
	v_lshl_add_u64 v[188:189], v[148:149], 0, v[184:185]
	v_lshl_add_u64 v[192:193], v[182:183], 0, v[146:147]
	v_lshl_add_u64 v[194:195], s[18:19], 0, v[186:187]
	global_load_dwordx4 v[182:185], v[188:189], off
	s_nop 0
	global_load_dwordx4 v[186:189], v[188:189], off offset:256
	v_lshl_add_u64 v[194:195], v[194:195], 0, v[146:147]
	s_and_b64 vcc, exec, s[0:1]
	s_mov_b64 s[0:1], -1
	v_readlane_b32 s45, v242, 41
	v_readlane_b32 s46, v242, 42
	v_readlane_b32 s47, v242, 43
	v_readlane_b32 s48, v242, 44
	v_readlane_b32 s49, v242, 45
	v_readlane_b32 s50, v242, 46
	v_readlane_b32 s51, v242, 47
	v_readlane_b32 s52, v242, 48
	v_readlane_b32 s53, v242, 49
	v_readlane_b32 s54, v242, 50
	v_readlane_b32 s55, v242, 51
	v_readlane_b32 s56, v242, 52
	v_readlane_b32 s57, v242, 53
	s_waitcnt vmcnt(0)
	v_lshlrev_b32_e32 v196, 16, v158
	v_and_b32_e32 v197, 0xffff0000, v158
	v_lshlrev_b32_e32 v158, 16, v159
	v_and_b32_e32 v159, 0xffff0000, v159
	v_lshlrev_b32_e32 v198, 16, v160
	v_and_b32_e32 v199, 0xffff0000, v160
	v_lshlrev_b32_e32 v208, 16, v170
	v_and_b32_e32 v209, 0xffff0000, v170
	v_lshlrev_b32_e32 v170, 16, v171
	v_and_b32_e32 v171, 0xffff0000, v171
	v_lshlrev_b32_e32 v210, 16, v172
	v_and_b32_e32 v211, 0xffff0000, v172
	v_lshlrev_b32_e32 v160, 16, v161
	v_and_b32_e32 v161, 0xffff0000, v161
	v_lshlrev_b32_e32 v200, 16, v162
	v_and_b32_e32 v201, 0xffff0000, v162
	v_lshlrev_b32_e32 v162, 16, v163
	v_and_b32_e32 v163, 0xffff0000, v163
	v_lshlrev_b32_e32 v202, 16, v164
	v_and_b32_e32 v203, 0xffff0000, v164
	v_lshlrev_b32_e32 v164, 16, v165
	v_and_b32_e32 v165, 0xffff0000, v165
	v_lshlrev_b32_e32 v204, 16, v166
	v_and_b32_e32 v205, 0xffff0000, v166
	v_lshlrev_b32_e32 v166, 16, v167
	v_and_b32_e32 v167, 0xffff0000, v167
	v_lshlrev_b32_e32 v206, 16, v168
	v_and_b32_e32 v207, 0xffff0000, v168
	v_lshlrev_b32_e32 v168, 16, v169
	v_and_b32_e32 v169, 0xffff0000, v169
	v_lshlrev_b32_e32 v172, 16, v173
	v_and_b32_e32 v173, 0xffff0000, v173
	v_pk_fma_f32 v[126:127], v[126:127], 0.5, v[158:159] op_sel_hi:[1,0,1]
	v_pk_fma_f32 v[124:125], v[124:125], 0.5, v[196:197] op_sel_hi:[1,0,1]
	v_pk_fma_f32 v[102:103], v[102:103], 0.5, v[170:171] op_sel_hi:[1,0,1]
	v_pk_fma_f32 v[100:101], v[100:101], 0.5, v[208:209] op_sel_hi:[1,0,1]
	v_pk_fma_f32 v[92:93], v[92:93], 0.5, v[210:211] op_sel_hi:[1,0,1]
	v_pk_fma_f32 v[122:123], v[122:123], 0.5, v[160:161] op_sel_hi:[1,0,1]
	v_pk_fma_f32 v[120:121], v[120:121], 0.5, v[198:199] op_sel_hi:[1,0,1]
	v_pk_fma_f32 v[110:111], v[110:111], 0.5, v[162:163] op_sel_hi:[1,0,1]
	v_pk_fma_f32 v[108:109], v[108:109], 0.5, v[200:201] op_sel_hi:[1,0,1]
	v_pk_fma_f32 v[106:107], v[106:107], 0.5, v[164:165] op_sel_hi:[1,0,1]
	v_pk_fma_f32 v[104:105], v[104:105], 0.5, v[202:203] op_sel_hi:[1,0,1]
	v_pk_fma_f32 v[118:119], v[118:119], 0.5, v[166:167] op_sel_hi:[1,0,1]
	v_pk_fma_f32 v[116:117], v[116:117], 0.5, v[204:205] op_sel_hi:[1,0,1]
	v_pk_fma_f32 v[114:115], v[114:115], 0.5, v[168:169] op_sel_hi:[1,0,1]
	v_pk_fma_f32 v[112:113], v[112:113], 0.5, v[206:207] op_sel_hi:[1,0,1]
	global_store_dwordx4 v[192:193], v[124:127], off nt
	global_store_dwordx4 v[192:193], v[120:123], off offset:16 nt
	global_store_dwordx4 v[192:193], v[108:111], off offset:512 nt
	global_store_dwordx4 v[192:193], v[104:107], off offset:528 nt
	global_store_dwordx4 v[194:195], v[116:119], off nt
	global_store_dwordx4 v[194:195], v[112:115], off offset:16 nt
	v_pk_fma_f32 v[94:95], v[94:95], 0.5, v[172:173] op_sel_hi:[1,0,1]
	global_store_dwordx4 v[194:195], v[100:103], off offset:512 nt
	global_store_dwordx4 v[194:195], v[92:95], off offset:528 nt
	s_nop 0
	v_lshlrev_b32_e32 v100, 16, v176
	v_lshlrev_b32_e32 v92, 16, v174
	v_and_b32_e32 v93, 0xffff0000, v174
	v_pk_fma_f32 v[92:93], v[96:97], 0.5, v[92:93] op_sel_hi:[1,0,1]
	v_lshlrev_b64 v[96:97], 12, v[190:191]
	v_lshlrev_b32_e32 v94, 16, v175
	v_and_b32_e32 v95, 0xffff0000, v175
	v_and_b32_e32 v101, 0xffff0000, v176
	v_lshlrev_b32_e32 v102, 16, v177
	v_and_b32_e32 v103, 0xffff0000, v177
	v_lshl_add_u64 v[96:97], s[18:19], 0, v[96:97]
	v_pk_fma_f32 v[94:95], v[98:99], 0.5, v[94:95] op_sel_hi:[1,0,1]
	v_pk_fma_f32 v[90:91], v[90:91], 0.5, v[102:103] op_sel_hi:[1,0,1]
	v_pk_fma_f32 v[88:89], v[88:89], 0.5, v[100:101] op_sel_hi:[1,0,1]
	v_lshl_add_u64 v[96:97], v[96:97], 0, v[146:147]
	global_store_dwordx4 v[96:97], v[92:95], off nt
	global_store_dwordx4 v[96:97], v[88:91], off offset:16 nt
	v_add_u32_e32 v98, 0x90, v150
	v_lshlrev_b32_e32 v92, 16, v180
	v_lshlrev_b32_e32 v88, 16, v178
	v_and_b32_e32 v89, 0xffff0000, v178
	v_lshlrev_b32_e32 v90, 16, v179
	v_and_b32_e32 v91, 0xffff0000, v179
	v_and_b32_e32 v93, 0xffff0000, v180
	v_lshlrev_b32_e32 v94, 16, v181
	v_and_b32_e32 v95, 0xffff0000, v181
	v_pk_fma_f32 v[86:87], v[86:87], 0.5, v[90:91] op_sel_hi:[1,0,1]
	v_pk_fma_f32 v[84:85], v[84:85], 0.5, v[88:89] op_sel_hi:[1,0,1]
	v_pk_fma_f32 v[76:77], v[76:77], 0.5, v[92:93] op_sel_hi:[1,0,1]
	v_pk_fma_f32 v[78:79], v[78:79], 0.5, v[94:95] op_sel_hi:[1,0,1]
	global_store_dwordx4 v[96:97], v[84:87], off offset:512 nt
	global_store_dwordx4 v[96:97], v[76:79], off offset:528 nt
	v_add_u32_e32 v96, 0x80, v150
	v_lshlrev_b32_e32 v84, 16, v184
	v_lshlrev_b32_e32 v76, 16, v182
	v_and_b32_e32 v77, 0xffff0000, v182
	v_pk_fma_f32 v[76:77], v[80:81], 0.5, v[76:77] op_sel_hi:[1,0,1]
	v_lshlrev_b64 v[80:81], 12, v[152:153]
	v_lshlrev_b32_e32 v78, 16, v183
	v_and_b32_e32 v79, 0xffff0000, v183
	v_and_b32_e32 v85, 0xffff0000, v184
	v_lshlrev_b32_e32 v86, 16, v185
	v_and_b32_e32 v87, 0xffff0000, v185
	v_lshl_add_u64 v[80:81], s[18:19], 0, v[80:81]
	v_pk_fma_f32 v[78:79], v[82:83], 0.5, v[78:79] op_sel_hi:[1,0,1]
	v_pk_fma_f32 v[74:75], v[74:75], 0.5, v[86:87] op_sel_hi:[1,0,1]
	v_pk_fma_f32 v[72:73], v[72:73], 0.5, v[84:85] op_sel_hi:[1,0,1]
	v_lshl_add_u64 v[80:81], v[80:81], 0, v[146:147]
	global_store_dwordx4 v[80:81], v[76:79], off nt
	global_store_dwordx4 v[80:81], v[72:75], off offset:16 nt
	v_ashrrev_i32_e32 v97, 31, v96
	v_lshlrev_b32_e32 v76, 16, v188
	v_lshlrev_b32_e32 v72, 16, v186
	v_and_b32_e32 v73, 0xffff0000, v186
	v_lshlrev_b32_e32 v74, 16, v187
	v_and_b32_e32 v75, 0xffff0000, v187
	v_and_b32_e32 v77, 0xffff0000, v188
	v_lshlrev_b32_e32 v78, 16, v189
	v_and_b32_e32 v79, 0xffff0000, v189
	v_pk_fma_f32 v[70:71], v[70:71], 0.5, v[74:75] op_sel_hi:[1,0,1]
	v_pk_fma_f32 v[68:69], v[68:69], 0.5, v[72:73] op_sel_hi:[1,0,1]
	v_pk_fma_f32 v[64:65], v[64:65], 0.5, v[76:77] op_sel_hi:[1,0,1]
	v_pk_fma_f32 v[66:67], v[66:67], 0.5, v[78:79] op_sel_hi:[1,0,1]
	global_store_dwordx4 v[80:81], v[68:71], off offset:512 nt
	global_store_dwordx4 v[80:81], v[64:67], off offset:528 nt
	v_ashrrev_i32_e32 v99, 31, v98
	v_add_u32_e32 v100, 0xa0, v150
	v_lshlrev_b64 v[64:65], 11, v[96:97]
	v_lshl_add_u64 v[64:65], v[148:149], 0, v[64:65]
	global_load_dwordx4 v[68:71], v[64:65], off
	global_load_dwordx4 v[72:75], v[64:65], off offset:256
	v_lshlrev_b64 v[64:65], 11, v[98:99]
	v_lshl_add_u64 v[64:65], v[148:149], 0, v[64:65]
	global_load_dwordx4 v[76:79], v[64:65], off
	global_load_dwordx4 v[80:83], v[64:65], off offset:256
	v_ashrrev_i32_e32 v101, 31, v100
	v_lshlrev_b64 v[64:65], 11, v[100:101]
	v_lshl_add_u64 v[64:65], v[148:149], 0, v[64:65]
	global_load_dwordx4 v[84:87], v[64:65], off
	global_load_dwordx4 v[88:91], v[64:65], off offset:256
	v_add_u32_e32 v102, 0xb0, v150
	v_ashrrev_i32_e32 v103, 31, v102
	v_lshlrev_b64 v[64:65], 11, v[102:103]
	v_lshl_add_u64 v[64:65], v[148:149], 0, v[64:65]
	global_load_dwordx4 v[92:95], v[64:65], off
	s_nop 0
	global_load_dwordx4 v[64:67], v[64:65], off offset:256
	s_waitcnt vmcnt(7)
	v_lshlrev_b32_e32 v104, 16, v68
	v_and_b32_e32 v105, 0xffff0000, v68
	v_lshlrev_b32_e32 v68, 16, v69
	v_and_b32_e32 v69, 0xffff0000, v69
	v_pk_fma_f32 v[62:63], v[62:63], 0.5, v[68:69] op_sel_hi:[1,0,1]
	v_lshlrev_b64 v[68:69], 12, v[96:97]
	v_lshlrev_b32_e32 v106, 16, v70
	v_and_b32_e32 v107, 0xffff0000, v70
	v_lshlrev_b32_e32 v70, 16, v71
	v_and_b32_e32 v71, 0xffff0000, v71
	v_lshl_add_u64 v[68:69], s[18:19], 0, v[68:69]
	v_pk_fma_f32 v[60:61], v[60:61], 0.5, v[104:105] op_sel_hi:[1,0,1]
	v_pk_fma_f32 v[58:59], v[58:59], 0.5, v[70:71] op_sel_hi:[1,0,1]
	v_pk_fma_f32 v[56:57], v[56:57], 0.5, v[106:107] op_sel_hi:[1,0,1]
	v_lshl_add_u64 v[68:69], v[68:69], 0, v[146:147]
	global_store_dwordx4 v[68:69], v[60:63], off nt
	global_store_dwordx4 v[68:69], v[56:59], off offset:16 nt
	s_waitcnt vmcnt(8)
	v_lshlrev_b32_e32 v60, 16, v74
	v_lshlrev_b32_e32 v56, 16, v72
	v_and_b32_e32 v57, 0xffff0000, v72
	v_lshlrev_b32_e32 v58, 16, v73
	v_and_b32_e32 v59, 0xffff0000, v73
	v_and_b32_e32 v61, 0xffff0000, v74
	v_lshlrev_b32_e32 v62, 16, v75
	v_and_b32_e32 v63, 0xffff0000, v75
	v_pk_fma_f32 v[54:55], v[54:55], 0.5, v[58:59] op_sel_hi:[1,0,1]
	v_pk_fma_f32 v[52:53], v[52:53], 0.5, v[56:57] op_sel_hi:[1,0,1]
	v_pk_fma_f32 v[44:45], v[44:45], 0.5, v[60:61] op_sel_hi:[1,0,1]
	v_pk_fma_f32 v[46:47], v[46:47], 0.5, v[62:63] op_sel_hi:[1,0,1]
	global_store_dwordx4 v[68:69], v[52:55], off offset:512 nt
	global_store_dwordx4 v[68:69], v[44:47], off offset:528 nt
	s_waitcnt vmcnt(9)
	v_lshlrev_b32_e32 v52, 16, v78
	v_lshlrev_b32_e32 v44, 16, v76
	v_and_b32_e32 v45, 0xffff0000, v76
	v_pk_fma_f32 v[44:45], v[48:49], 0.5, v[44:45] op_sel_hi:[1,0,1]
	v_lshlrev_b64 v[48:49], 12, v[98:99]
	v_lshlrev_b32_e32 v46, 16, v77
	v_and_b32_e32 v47, 0xffff0000, v77
	v_and_b32_e32 v53, 0xffff0000, v78
	v_lshlrev_b32_e32 v54, 16, v79
	v_and_b32_e32 v55, 0xffff0000, v79
	v_lshl_add_u64 v[48:49], s[18:19], 0, v[48:49]
	v_pk_fma_f32 v[46:47], v[50:51], 0.5, v[46:47] op_sel_hi:[1,0,1]
	v_pk_fma_f32 v[42:43], v[42:43], 0.5, v[54:55] op_sel_hi:[1,0,1]
	v_pk_fma_f32 v[40:41], v[40:41], 0.5, v[52:53] op_sel_hi:[1,0,1]
	v_lshl_add_u64 v[48:49], v[48:49], 0, v[146:147]
	global_store_dwordx4 v[48:49], v[44:47], off nt
	global_store_dwordx4 v[48:49], v[40:43], off offset:16 nt
	s_waitcnt vmcnt(10)
	v_lshlrev_b32_e32 v44, 16, v82
	v_lshlrev_b32_e32 v40, 16, v80
	v_and_b32_e32 v41, 0xffff0000, v80
	v_lshlrev_b32_e32 v42, 16, v81
	v_and_b32_e32 v43, 0xffff0000, v81
	v_and_b32_e32 v45, 0xffff0000, v82
	v_lshlrev_b32_e32 v46, 16, v83
	v_and_b32_e32 v47, 0xffff0000, v83
	v_pk_fma_f32 v[38:39], v[38:39], 0.5, v[42:43] op_sel_hi:[1,0,1]
	v_pk_fma_f32 v[36:37], v[36:37], 0.5, v[40:41] op_sel_hi:[1,0,1]
	v_pk_fma_f32 v[28:29], v[28:29], 0.5, v[44:45] op_sel_hi:[1,0,1]
	v_pk_fma_f32 v[30:31], v[30:31], 0.5, v[46:47] op_sel_hi:[1,0,1]
	global_store_dwordx4 v[48:49], v[36:39], off offset:512 nt
	global_store_dwordx4 v[48:49], v[28:31], off offset:528 nt
	s_waitcnt vmcnt(11)
	v_lshlrev_b32_e32 v36, 16, v86
	v_lshlrev_b32_e32 v28, 16, v84
	v_and_b32_e32 v29, 0xffff0000, v84
	v_pk_fma_f32 v[28:29], v[32:33], 0.5, v[28:29] op_sel_hi:[1,0,1]
	v_lshlrev_b64 v[32:33], 12, v[100:101]
	v_lshlrev_b32_e32 v30, 16, v85
	v_and_b32_e32 v31, 0xffff0000, v85
	v_and_b32_e32 v37, 0xffff0000, v86
	v_lshlrev_b32_e32 v38, 16, v87
	v_and_b32_e32 v39, 0xffff0000, v87
	v_lshl_add_u64 v[32:33], s[18:19], 0, v[32:33]
	v_pk_fma_f32 v[30:31], v[34:35], 0.5, v[30:31] op_sel_hi:[1,0,1]
	v_pk_fma_f32 v[26:27], v[26:27], 0.5, v[38:39] op_sel_hi:[1,0,1]
	v_pk_fma_f32 v[24:25], v[24:25], 0.5, v[36:37] op_sel_hi:[1,0,1]
	v_lshl_add_u64 v[32:33], v[32:33], 0, v[146:147]
	global_store_dwordx4 v[32:33], v[28:31], off nt
	global_store_dwordx4 v[32:33], v[24:27], off offset:16 nt
	s_waitcnt vmcnt(12)
	v_lshlrev_b32_e32 v28, 16, v90
	v_lshlrev_b32_e32 v24, 16, v88
	v_and_b32_e32 v25, 0xffff0000, v88
	v_lshlrev_b32_e32 v26, 16, v89
	v_and_b32_e32 v27, 0xffff0000, v89
	v_and_b32_e32 v29, 0xffff0000, v90
	v_lshlrev_b32_e32 v30, 16, v91
	v_and_b32_e32 v31, 0xffff0000, v91
	v_pk_fma_f32 v[22:23], v[22:23], 0.5, v[26:27] op_sel_hi:[1,0,1]
	v_pk_fma_f32 v[20:21], v[20:21], 0.5, v[24:25] op_sel_hi:[1,0,1]
	v_pk_fma_f32 v[12:13], v[12:13], 0.5, v[28:29] op_sel_hi:[1,0,1]
	v_pk_fma_f32 v[14:15], v[14:15], 0.5, v[30:31] op_sel_hi:[1,0,1]
	global_store_dwordx4 v[32:33], v[20:23], off offset:512 nt
	global_store_dwordx4 v[32:33], v[12:15], off offset:528 nt
	s_waitcnt vmcnt(13)
	v_lshlrev_b32_e32 v20, 16, v94
	v_lshlrev_b32_e32 v12, 16, v92
	v_and_b32_e32 v13, 0xffff0000, v92
	v_pk_fma_f32 v[12:13], v[16:17], 0.5, v[12:13] op_sel_hi:[1,0,1]
	v_lshlrev_b64 v[16:17], 12, v[102:103]
	v_lshlrev_b32_e32 v14, 16, v93
	v_and_b32_e32 v15, 0xffff0000, v93
	v_and_b32_e32 v21, 0xffff0000, v94
	v_lshlrev_b32_e32 v22, 16, v95
	v_and_b32_e32 v23, 0xffff0000, v95
	v_lshl_add_u64 v[16:17], s[18:19], 0, v[16:17]
	v_pk_fma_f32 v[14:15], v[18:19], 0.5, v[14:15] op_sel_hi:[1,0,1]
	v_pk_fma_f32 v[10:11], v[10:11], 0.5, v[22:23] op_sel_hi:[1,0,1]
	v_pk_fma_f32 v[8:9], v[8:9], 0.5, v[20:21] op_sel_hi:[1,0,1]
	v_lshl_add_u64 v[16:17], v[16:17], 0, v[146:147]
	global_store_dwordx4 v[16:17], v[12:15], off nt
	global_store_dwordx4 v[16:17], v[8:11], off offset:16 nt
	s_waitcnt vmcnt(14)
	v_lshlrev_b32_e32 v12, 16, v66
	v_lshlrev_b32_e32 v8, 16, v64
	v_and_b32_e32 v9, 0xffff0000, v64
	v_lshlrev_b32_e32 v10, 16, v65
	v_and_b32_e32 v11, 0xffff0000, v65
	v_and_b32_e32 v13, 0xffff0000, v66
	v_lshlrev_b32_e32 v14, 16, v67
	v_and_b32_e32 v15, 0xffff0000, v67
	v_pk_fma_f32 v[6:7], v[6:7], 0.5, v[10:11] op_sel_hi:[1,0,1]
	v_pk_fma_f32 v[4:5], v[4:5], 0.5, v[8:9] op_sel_hi:[1,0,1]
	v_pk_fma_f32 v[2:3], v[2:3], 0.5, v[14:15] op_sel_hi:[1,0,1]
	v_pk_fma_f32 v[0:1], v[0:1], 0.5, v[12:13] op_sel_hi:[1,0,1]
	global_store_dwordx4 v[16:17], v[4:7], off offset:512 nt
	global_store_dwordx4 v[16:17], v[0:3], off offset:528 nt
	s_cbranch_vccnz .LBB0_2046
	s_andn2_b64 vcc, exec, s[8:9]
	s_cbranch_vccnz .LBB0_2045
	s_barrier
	s_branch .LBB0_2045
